# RESID epilogues with 16B residual loads/stores (perm32 weight rows for w_o/w_ffn_out, loads batched), attention LDS batching, barrier leader release reorder
# speedup vs baseline: 1.0292x; 1.0231x over previous
.LBB0_63:
	s_or_b64 exec, exec, s[2:3]
	s_waitcnt lgkmcnt(0)
	s_barrier
	ds_read_b32 v2, v37
	s_mov_b64 s[2:3], -1
	s_waitcnt lgkmcnt(0)
	v_cmp_lt_i32_e32 vcc, s9, v2
	v_readfirstlane_b32 s29, v2
	s_cbranch_vccnz .LBB0_58
	s_sub_u32 s34, s29, 0x680
	s_cmpk_lt_u32 s34, 0x2c0
	s_cselect_b32 s34, 1, 0
	s_cmpk_gt_u32 s29, 0x9df
	s_cselect_b32 s35, 1, 0
	s_or_b32 s34, s34, s35
	s_cmpk_gt_i32 s29, 0xff
	s_mov_b64 s[26:27], -1
	s_cbranch_scc0 .LBB0_83
	s_mov_b64 s[22:23], -1
	s_cmpk_gt_u32 s29, 0x67f
	s_cbranch_scc0 .LBB0_80
	s_cmpk_gt_u32 s29, 0x93f
	s_cbranch_scc0 .LBB0_77
	s_cmpk_gt_u32 s29, 0x97f
	s_cbranch_scc0 .LBB0_74
	s_cmpk_gt_u32 s29, 0x99f
	s_cbranch_scc0 .LBB0_104
	s_cmpk_gt_u32 s29, 0x9df
	s_mov_b64 s[2:3], -1
	s_cbranch_scc0 .LBB0_105
	s_add_i32 s2, s29, 0xfffff620
	s_lshr_b32 s18, s2, 6
	v_readlane_b32 s36, v253, 0
	s_and_b32 s28, s2, 63
	s_lshl_b64 s[2:3], s[18:19], 22
	v_readlane_b32 s40, v253, 4
	v_readlane_b32 s41, v253, 5
	s_add_u32 s12, s40, s2
	v_readlane_b32 s37, v253, 1
	v_readlane_b32 s38, v253, 2
	v_readlane_b32 s39, v253, 3
	v_readlane_b32 s42, v253, 6
	v_readlane_b32 s43, v253, 7
	s_addc_u32 s13, s41, s3
	s_lshl_b64 s[2:3], s[18:19], 21
	v_readlane_b32 s15, v254, 3
	v_readlane_b32 s36, v253, 16
	s_add_u32 s20, s15, s2
	v_readlane_b32 s2, v254, 4
	v_readlane_b32 s37, v253, 17
	v_readlane_b32 s38, v253, 18
	v_readlane_b32 s39, v253, 19
	v_readlane_b32 s40, v253, 20
	v_readlane_b32 s41, v253, 21
	v_readlane_b32 s42, v253, 22
	v_readlane_b32 s43, v253, 23
	v_readlane_b32 s44, v253, 24
	v_readlane_b32 s45, v253, 25
	v_readlane_b32 s46, v253, 26
	v_readlane_b32 s47, v253, 27
	v_readlane_b32 s48, v253, 28
	v_readlane_b32 s49, v253, 29
	v_readlane_b32 s50, v253, 30
	v_readlane_b32 s51, v253, 31
	s_addc_u32 s21, s2, s3
	s_mov_b64 s[24:25], 0
	s_mov_b64 s[2:3], 0
	s_cbranch_execz .LBB0_106

.LBB0_87:
	v_or_b32_e32 v2, s18, v40
	s_cmp_eq_u32 s34, 0
	s_cbranch_scc1 .LBB0_88
	v_and_b32_e32 v2, 0xe0, v40
	v_lshlrev_b32_e32 v3, 1, v40
	v_and_b32_e32 v3, 24, v3
	v_and_b32_e32 v4, 4, v39
	v_or3_b32 v2, v2, v3, v4
	v_or_b32_e32 v2, s18, v2

.LBB0_205:
	s_or_b64 exec, exec, s[4:5]
	s_mov_b64 s[4:5], exec
	v_mbcnt_lo_u32_b32 v0, s4, 0
	v_mbcnt_hi_u32_b32 v0, s5, v0
	v_cmp_eq_u32_e32 vcc, 0, v0
	s_and_saveexec_b64 s[6:7], vcc
	s_cbranch_execz .LBB0_207
	s_bcnt1_i32_b64 s4, s[4:5]
	v_mov_b32_e32 v0, 0x2000
	v_mov_b32_e32 v1, s4
	global_atomic_add v0, v1, s[2:3] offset:1024
.LBB0_207:
	s_or_b64 exec, exec, s[6:7]
	buffer_inv sc1
	s_waitcnt vmcnt(0)

.LBB0_281:
	s_or_b64 exec, exec, s[4:5]
	s_mov_b64 s[4:5], exec
	v_mbcnt_lo_u32_b32 v0, s4, 0
	v_mbcnt_hi_u32_b32 v0, s5, v0
	v_cmp_eq_u32_e32 vcc, 0, v0
	s_and_saveexec_b64 s[6:7], vcc
	s_cbranch_execz .LBB0_283
	s_bcnt1_i32_b64 s4, s[4:5]
	v_mov_b32_e32 v0, s4
	global_atomic_add v183, v0, s[2:3] offset:1024

.LBB0_1474:
	v_mov_b32_e32 v112, v180
	s_barrier
	v_mov_b32_e32 v130, v180
	v_ashrrev_i32_e32 v131, 2, v112
	v_and_b32_e32 v131, 0xffffffc0, v131
	v_add_u32_e32 v131, s4, v131
	v_and_or_b32 v132, v130, 15, v131
	v_lshrrev_b32_e32 v112, 1, v112
	v_lshrrev_b32_e32 v130, 1, v130
	v_and_b32_e32 v112, 0x60, v112
	v_and_b32_e32 v130, 24, v130
	v_or3_b32 v130, v112, v130, s2
	s_mul_i32 s2, s96, 0x500
	v_add_u32_e32 v134, 0xffff8000, v132
	s_ashr_i32 s3, s2, 31
	v_ashrrev_i32_e32 v135, 31, v134
	v_lshl_add_u64 v[134:135], v[134:135], 0, s[2:3]
	v_lshlrev_b64 v[134:135], 12, v[134:135]
	v_lshl_add_u64 v[134:135], s[74:75], 0, v[134:135]
	v_ashrrev_i32_e32 v131, 31, v130
	s_mov_b64 s[4:5], -1
	s_andn2_b64 vcc, exec, s[0:1]
	v_lshl_add_u64 v[136:137], v[130:131], 2, v[134:135]
	s_mov_b32 s97, 0x8000
	s_cbranch_vccnz .Lmy_wo_epi
	s_mov_b64 s[4:5], 0
	global_store_dwordx4 v[136:137], v[126:129], off

.Lmy_wo_epi:
	v_lshlrev_b32_e32 v134, 11, v132
	v_lshl_add_u32 v134, v130, 1, v134
	v_add_u32_e32 v135, 0x8000, v134
	v_add_u32_e32 v138, 0x10000, v134
	v_add_u32_e32 v139, 0x18000, v134
	v_add_u32_e32 v140, 0x40000, v134
	v_add_u32_e32 v141, 0x48000, v134
	v_add_u32_e32 v112, 0x50000, v134
	v_add_u32_e32 v133, 0x58000, v134
	global_load_dwordx4 v[192:195], v134, s[26:27]
	global_load_dwordx4 v[196:199], v134, s[26:27] offset:256
	global_load_dwordx4 v[200:203], v135, s[26:27]
	global_load_dwordx4 v[204:207], v135, s[26:27] offset:256
	global_load_dwordx4 v[208:211], v138, s[26:27]
	global_load_dwordx4 v[212:215], v138, s[26:27] offset:256
	global_load_dwordx4 v[216:219], v139, s[26:27]
	global_load_dwordx4 v[220:223], v139, s[26:27] offset:256
	global_load_dwordx4 v[224:227], v140, s[26:27]
	global_load_dwordx4 v[228:231], v140, s[26:27] offset:256
	global_load_dwordx4 v[232:235], v141, s[26:27]
	global_load_dwordx4 v[236:239], v141, s[26:27] offset:256
	global_load_dwordx4 v[240:243], v112, s[26:27]
	global_load_dwordx4 v[244:247], v112, s[26:27] offset:256
	global_load_dwordx4 v[248:251], v133, s[26:27]
	global_load_dwordx4 v[174:177], v133, s[26:27] offset:256
	s_waitcnt vmcnt(15)
	v_lshlrev_b32_e32 v178, 16, v192
	v_and_b32_e32 v179, 0xffff0000, v192
	v_pk_add_f32 v[126:127], v[126:127], v[178:179]
	v_lshlrev_b32_e32 v178, 16, v193
	v_and_b32_e32 v179, 0xffff0000, v193
	v_pk_add_f32 v[128:129], v[128:129], v[178:179]
	v_lshlrev_b32_e32 v178, 16, v194
	v_and_b32_e32 v179, 0xffff0000, v194
	v_pk_add_f32 v[122:123], v[122:123], v[178:179]
	v_lshlrev_b32_e32 v178, 16, v195
	v_and_b32_e32 v179, 0xffff0000, v195
	v_pk_add_f32 v[124:125], v[124:125], v[178:179]
	s_waitcnt vmcnt(14)
	v_lshlrev_b32_e32 v178, 16, v196
	v_and_b32_e32 v179, 0xffff0000, v196
	v_pk_add_f32 v[118:119], v[118:119], v[178:179]
	v_lshlrev_b32_e32 v178, 16, v197
	v_and_b32_e32 v179, 0xffff0000, v197
	v_pk_add_f32 v[120:121], v[120:121], v[178:179]
	v_lshlrev_b32_e32 v178, 16, v198
	v_and_b32_e32 v179, 0xffff0000, v198
	v_pk_add_f32 v[114:115], v[114:115], v[178:179]
	v_lshlrev_b32_e32 v178, 16, v199
	v_and_b32_e32 v179, 0xffff0000, v199
	v_pk_add_f32 v[116:117], v[116:117], v[178:179]
	s_waitcnt vmcnt(13)
	v_lshlrev_b32_e32 v178, 16, v200
	v_and_b32_e32 v179, 0xffff0000, v200
	v_pk_add_f32 v[108:109], v[108:109], v[178:179]
	v_lshlrev_b32_e32 v178, 16, v201
	v_and_b32_e32 v179, 0xffff0000, v201
	v_pk_add_f32 v[110:111], v[110:111], v[178:179]
	v_lshlrev_b32_e32 v178, 16, v202
	v_and_b32_e32 v179, 0xffff0000, v202
	v_pk_add_f32 v[104:105], v[104:105], v[178:179]
	v_lshlrev_b32_e32 v178, 16, v203
	v_and_b32_e32 v179, 0xffff0000, v203
	v_pk_add_f32 v[106:107], v[106:107], v[178:179]
	s_waitcnt vmcnt(12)
	v_lshlrev_b32_e32 v178, 16, v204
	v_and_b32_e32 v179, 0xffff0000, v204
	v_pk_add_f32 v[100:101], v[100:101], v[178:179]
	v_lshlrev_b32_e32 v178, 16, v205
	v_and_b32_e32 v179, 0xffff0000, v205
	v_pk_add_f32 v[102:103], v[102:103], v[178:179]
	v_lshlrev_b32_e32 v178, 16, v206
	v_and_b32_e32 v179, 0xffff0000, v206
	v_pk_add_f32 v[96:97], v[96:97], v[178:179]
	v_lshlrev_b32_e32 v178, 16, v207
	v_and_b32_e32 v179, 0xffff0000, v207
	v_pk_add_f32 v[98:99], v[98:99], v[178:179]
	s_waitcnt vmcnt(11)
	v_lshlrev_b32_e32 v178, 16, v208
	v_and_b32_e32 v179, 0xffff0000, v208
	v_pk_add_f32 v[92:93], v[92:93], v[178:179]
	v_lshlrev_b32_e32 v178, 16, v209
	v_and_b32_e32 v179, 0xffff0000, v209
	v_pk_add_f32 v[94:95], v[94:95], v[178:179]
	v_lshlrev_b32_e32 v178, 16, v210
	v_and_b32_e32 v179, 0xffff0000, v210
	v_pk_add_f32 v[88:89], v[88:89], v[178:179]
	v_lshlrev_b32_e32 v178, 16, v211
	v_and_b32_e32 v179, 0xffff0000, v211
	v_pk_add_f32 v[90:91], v[90:91], v[178:179]
	s_waitcnt vmcnt(10)
	v_lshlrev_b32_e32 v178, 16, v212
	v_and_b32_e32 v179, 0xffff0000, v212
	v_pk_add_f32 v[84:85], v[84:85], v[178:179]
	v_lshlrev_b32_e32 v178, 16, v213
	v_and_b32_e32 v179, 0xffff0000, v213
	v_pk_add_f32 v[86:87], v[86:87], v[178:179]
	v_lshlrev_b32_e32 v178, 16, v214
	v_and_b32_e32 v179, 0xffff0000, v214
	v_pk_add_f32 v[80:81], v[80:81], v[178:179]
	v_lshlrev_b32_e32 v178, 16, v215
	v_and_b32_e32 v179, 0xffff0000, v215
	v_pk_add_f32 v[82:83], v[82:83], v[178:179]
	s_waitcnt vmcnt(9)
	v_lshlrev_b32_e32 v178, 16, v216
	v_and_b32_e32 v179, 0xffff0000, v216
	v_pk_add_f32 v[76:77], v[76:77], v[178:179]
	v_lshlrev_b32_e32 v178, 16, v217
	v_and_b32_e32 v179, 0xffff0000, v217
	v_pk_add_f32 v[78:79], v[78:79], v[178:179]
	v_lshlrev_b32_e32 v178, 16, v218
	v_and_b32_e32 v179, 0xffff0000, v218
	v_pk_add_f32 v[72:73], v[72:73], v[178:179]
	v_lshlrev_b32_e32 v178, 16, v219
	v_and_b32_e32 v179, 0xffff0000, v219
	v_pk_add_f32 v[74:75], v[74:75], v[178:179]
	s_waitcnt vmcnt(8)
	v_lshlrev_b32_e32 v178, 16, v220
	v_and_b32_e32 v179, 0xffff0000, v220
	v_pk_add_f32 v[68:69], v[68:69], v[178:179]
	v_lshlrev_b32_e32 v178, 16, v221
	v_and_b32_e32 v179, 0xffff0000, v221
	v_pk_add_f32 v[70:71], v[70:71], v[178:179]
	v_lshlrev_b32_e32 v178, 16, v222
	v_and_b32_e32 v179, 0xffff0000, v222
	v_pk_add_f32 v[64:65], v[64:65], v[178:179]
	v_lshlrev_b32_e32 v178, 16, v223
	v_and_b32_e32 v179, 0xffff0000, v223
	v_pk_add_f32 v[66:67], v[66:67], v[178:179]
	s_waitcnt vmcnt(7)
	v_lshlrev_b32_e32 v178, 16, v224
	v_and_b32_e32 v179, 0xffff0000, v224
	v_pk_add_f32 v[60:61], v[60:61], v[178:179]
	v_lshlrev_b32_e32 v178, 16, v225
	v_and_b32_e32 v179, 0xffff0000, v225
	v_pk_add_f32 v[62:63], v[62:63], v[178:179]
	v_lshlrev_b32_e32 v178, 16, v226
	v_and_b32_e32 v179, 0xffff0000, v226
	v_pk_add_f32 v[56:57], v[56:57], v[178:179]
	v_lshlrev_b32_e32 v178, 16, v227
	v_and_b32_e32 v179, 0xffff0000, v227
	v_pk_add_f32 v[58:59], v[58:59], v[178:179]
	s_waitcnt vmcnt(6)
	v_lshlrev_b32_e32 v178, 16, v228
	v_and_b32_e32 v179, 0xffff0000, v228
	v_pk_add_f32 v[52:53], v[52:53], v[178:179]
	v_lshlrev_b32_e32 v178, 16, v229
	v_and_b32_e32 v179, 0xffff0000, v229
	v_pk_add_f32 v[54:55], v[54:55], v[178:179]
	v_lshlrev_b32_e32 v178, 16, v230
	v_and_b32_e32 v179, 0xffff0000, v230
	v_pk_add_f32 v[48:49], v[48:49], v[178:179]
	v_lshlrev_b32_e32 v178, 16, v231
	v_and_b32_e32 v179, 0xffff0000, v231
	v_pk_add_f32 v[50:51], v[50:51], v[178:179]
	s_waitcnt vmcnt(5)
	v_lshlrev_b32_e32 v178, 16, v232
	v_and_b32_e32 v179, 0xffff0000, v232
	v_pk_add_f32 v[44:45], v[44:45], v[178:179]
	v_lshlrev_b32_e32 v178, 16, v233
	v_and_b32_e32 v179, 0xffff0000, v233
	v_pk_add_f32 v[46:47], v[46:47], v[178:179]
	v_lshlrev_b32_e32 v178, 16, v234
	v_and_b32_e32 v179, 0xffff0000, v234
	v_pk_add_f32 v[40:41], v[40:41], v[178:179]
	v_lshlrev_b32_e32 v178, 16, v235
	v_and_b32_e32 v179, 0xffff0000, v235
	v_pk_add_f32 v[42:43], v[42:43], v[178:179]
	s_waitcnt vmcnt(4)
	v_lshlrev_b32_e32 v178, 16, v236
	v_and_b32_e32 v179, 0xffff0000, v236
	v_pk_add_f32 v[36:37], v[36:37], v[178:179]
	v_lshlrev_b32_e32 v178, 16, v237
	v_and_b32_e32 v179, 0xffff0000, v237
	v_pk_add_f32 v[38:39], v[38:39], v[178:179]
	v_lshlrev_b32_e32 v178, 16, v238
	v_and_b32_e32 v179, 0xffff0000, v238
	v_pk_add_f32 v[32:33], v[32:33], v[178:179]
	v_lshlrev_b32_e32 v178, 16, v239
	v_and_b32_e32 v179, 0xffff0000, v239
	v_pk_add_f32 v[34:35], v[34:35], v[178:179]
	s_waitcnt vmcnt(3)
	v_lshlrev_b32_e32 v178, 16, v240
	v_and_b32_e32 v179, 0xffff0000, v240
	v_pk_add_f32 v[28:29], v[28:29], v[178:179]
	v_lshlrev_b32_e32 v178, 16, v241
	v_and_b32_e32 v179, 0xffff0000, v241
	v_pk_add_f32 v[30:31], v[30:31], v[178:179]
	v_lshlrev_b32_e32 v178, 16, v242
	v_and_b32_e32 v179, 0xffff0000, v242
	v_pk_add_f32 v[24:25], v[24:25], v[178:179]
	v_lshlrev_b32_e32 v178, 16, v243
	v_and_b32_e32 v179, 0xffff0000, v243
	v_pk_add_f32 v[26:27], v[26:27], v[178:179]
	s_waitcnt vmcnt(2)
	v_lshlrev_b32_e32 v178, 16, v244
	v_and_b32_e32 v179, 0xffff0000, v244
	v_pk_add_f32 v[20:21], v[20:21], v[178:179]
	v_lshlrev_b32_e32 v178, 16, v245
	v_and_b32_e32 v179, 0xffff0000, v245
	v_pk_add_f32 v[22:23], v[22:23], v[178:179]
	v_lshlrev_b32_e32 v178, 16, v246
	v_and_b32_e32 v179, 0xffff0000, v246
	v_pk_add_f32 v[16:17], v[16:17], v[178:179]
	v_lshlrev_b32_e32 v178, 16, v247
	v_and_b32_e32 v179, 0xffff0000, v247
	v_pk_add_f32 v[18:19], v[18:19], v[178:179]
	s_waitcnt vmcnt(1)
	v_lshlrev_b32_e32 v178, 16, v248
	v_and_b32_e32 v179, 0xffff0000, v248
	v_pk_add_f32 v[12:13], v[12:13], v[178:179]
	v_lshlrev_b32_e32 v178, 16, v249
	v_and_b32_e32 v179, 0xffff0000, v249
	v_pk_add_f32 v[14:15], v[14:15], v[178:179]
	v_lshlrev_b32_e32 v178, 16, v250
	v_and_b32_e32 v179, 0xffff0000, v250
	v_pk_add_f32 v[8:9], v[8:9], v[178:179]
	v_lshlrev_b32_e32 v178, 16, v251
	v_and_b32_e32 v179, 0xffff0000, v251
	v_pk_add_f32 v[10:11], v[10:11], v[178:179]
	s_waitcnt vmcnt(0)
	v_lshlrev_b32_e32 v178, 16, v174
	v_and_b32_e32 v179, 0xffff0000, v174
	v_pk_add_f32 v[4:5], v[4:5], v[178:179]
	v_lshlrev_b32_e32 v178, 16, v175
	v_and_b32_e32 v179, 0xffff0000, v175
	v_pk_add_f32 v[6:7], v[6:7], v[178:179]
	v_lshlrev_b32_e32 v178, 16, v176
	v_and_b32_e32 v179, 0xffff0000, v176
	v_pk_add_f32 v[0:1], v[0:1], v[178:179]
	v_lshlrev_b32_e32 v178, 16, v177
	v_and_b32_e32 v179, 0xffff0000, v177
	v_pk_add_f32 v[2:3], v[2:3], v[178:179]
	v_cvt_pk_bf16_f32 v192, v126, v127
	v_cvt_pk_bf16_f32 v193, v128, v129
	v_cvt_pk_bf16_f32 v194, v122, v123
	v_cvt_pk_bf16_f32 v195, v124, v125
	global_store_dwordx4 v134, v[192:195], s[26:27]
	v_cvt_pk_bf16_f32 v196, v118, v119
	v_cvt_pk_bf16_f32 v197, v120, v121
	v_cvt_pk_bf16_f32 v198, v114, v115
	v_cvt_pk_bf16_f32 v199, v116, v117
	global_store_dwordx4 v134, v[196:199], s[26:27] offset:256
	v_cvt_pk_bf16_f32 v200, v108, v109
	v_cvt_pk_bf16_f32 v201, v110, v111
	v_cvt_pk_bf16_f32 v202, v104, v105
	v_cvt_pk_bf16_f32 v203, v106, v107
	global_store_dwordx4 v135, v[200:203], s[26:27]
	v_cvt_pk_bf16_f32 v204, v100, v101
	v_cvt_pk_bf16_f32 v205, v102, v103
	v_cvt_pk_bf16_f32 v206, v96, v97
	v_cvt_pk_bf16_f32 v207, v98, v99
	global_store_dwordx4 v135, v[204:207], s[26:27] offset:256
	v_cvt_pk_bf16_f32 v208, v92, v93
	v_cvt_pk_bf16_f32 v209, v94, v95
	v_cvt_pk_bf16_f32 v210, v88, v89
	v_cvt_pk_bf16_f32 v211, v90, v91
	global_store_dwordx4 v138, v[208:211], s[26:27]
	v_cvt_pk_bf16_f32 v212, v84, v85
	v_cvt_pk_bf16_f32 v213, v86, v87
	v_cvt_pk_bf16_f32 v214, v80, v81
	v_cvt_pk_bf16_f32 v215, v82, v83
	global_store_dwordx4 v138, v[212:215], s[26:27] offset:256
	v_cvt_pk_bf16_f32 v216, v76, v77
	v_cvt_pk_bf16_f32 v217, v78, v79
	v_cvt_pk_bf16_f32 v218, v72, v73
	v_cvt_pk_bf16_f32 v219, v74, v75
	global_store_dwordx4 v139, v[216:219], s[26:27]
	v_cvt_pk_bf16_f32 v220, v68, v69
	v_cvt_pk_bf16_f32 v221, v70, v71
	v_cvt_pk_bf16_f32 v222, v64, v65
	v_cvt_pk_bf16_f32 v223, v66, v67
	global_store_dwordx4 v139, v[220:223], s[26:27] offset:256
	v_cvt_pk_bf16_f32 v224, v60, v61
	v_cvt_pk_bf16_f32 v225, v62, v63
	v_cvt_pk_bf16_f32 v226, v56, v57
	v_cvt_pk_bf16_f32 v227, v58, v59
	global_store_dwordx4 v140, v[224:227], s[26:27]
	v_cvt_pk_bf16_f32 v228, v52, v53
	v_cvt_pk_bf16_f32 v229, v54, v55
	v_cvt_pk_bf16_f32 v230, v48, v49
	v_cvt_pk_bf16_f32 v231, v50, v51
	global_store_dwordx4 v140, v[228:231], s[26:27] offset:256
	v_cvt_pk_bf16_f32 v232, v44, v45
	v_cvt_pk_bf16_f32 v233, v46, v47
	v_cvt_pk_bf16_f32 v234, v40, v41
	v_cvt_pk_bf16_f32 v235, v42, v43
	global_store_dwordx4 v141, v[232:235], s[26:27]
	v_cvt_pk_bf16_f32 v236, v36, v37
	v_cvt_pk_bf16_f32 v237, v38, v39
	v_cvt_pk_bf16_f32 v238, v32, v33
	v_cvt_pk_bf16_f32 v239, v34, v35
	global_store_dwordx4 v141, v[236:239], s[26:27] offset:256
	v_cvt_pk_bf16_f32 v240, v28, v29
	v_cvt_pk_bf16_f32 v241, v30, v31
	v_cvt_pk_bf16_f32 v242, v24, v25
	v_cvt_pk_bf16_f32 v243, v26, v27
	global_store_dwordx4 v112, v[240:243], s[26:27]
	v_cvt_pk_bf16_f32 v244, v20, v21
	v_cvt_pk_bf16_f32 v245, v22, v23
	v_cvt_pk_bf16_f32 v246, v16, v17
	v_cvt_pk_bf16_f32 v247, v18, v19
	global_store_dwordx4 v112, v[244:247], s[26:27] offset:256
	v_cvt_pk_bf16_f32 v248, v12, v13
	v_cvt_pk_bf16_f32 v249, v14, v15
	v_cvt_pk_bf16_f32 v250, v8, v9
	v_cvt_pk_bf16_f32 v251, v10, v11
	global_store_dwordx4 v133, v[248:251], s[26:27]
	v_cvt_pk_bf16_f32 v174, v4, v5
	v_cvt_pk_bf16_f32 v175, v6, v7
	v_cvt_pk_bf16_f32 v176, v0, v1
	v_cvt_pk_bf16_f32 v177, v2, v3
	global_store_dwordx4 v133, v[174:177], s[26:27] offset:256
	s_branch .LBB0_1554

.LBB0_1558:
	global_store_dwordx4 v[136:137], v[122:125], off offset:16
	s_cbranch_execz .LBB0_1479

.LBB0_1562:
	global_store_dwordx4 v[136:137], v[114:117], off offset:528
	s_cbranch_execz .LBB0_1483
	s_branch .LBB0_1484

.LBB0_1564:
	global_store_dwordx4 v[116:117], v[104:107], off offset:16
	s_cbranch_execz .LBB0_1489

.LBB0_1568:
	global_store_dwordx4 v[116:117], v[96:99], off offset:528
	s_cbranch_execz .LBB0_1493
	s_branch .LBB0_1494

.LBB0_1570:
	global_store_dwordx4 v[98:99], v[88:91], off offset:16
	s_cbranch_execz .LBB0_1499

.LBB0_1574:
	global_store_dwordx4 v[98:99], v[80:83], off offset:528
	s_cbranch_execz .LBB0_1503
	s_branch .LBB0_1504

.LBB0_1576:
	global_store_dwordx4 v[82:83], v[72:75], off offset:16
	s_cbranch_execz .LBB0_1509

.LBB0_1580:
	global_store_dwordx4 v[82:83], v[64:67], off offset:528
	s_cbranch_execz .LBB0_1513
	s_branch .LBB0_1514

.LBB0_1582:
	global_store_dwordx4 v[66:67], v[56:59], off offset:16
	s_cbranch_execz .LBB0_1519

.LBB0_1586:
	global_store_dwordx4 v[66:67], v[48:51], off offset:528
	s_cbranch_execz .LBB0_1523
	s_branch .LBB0_1524

.LBB0_1588:
	global_store_dwordx4 v[50:51], v[40:43], off offset:16
	s_cbranch_execz .LBB0_1529

.LBB0_1592:
	global_store_dwordx4 v[50:51], v[32:35], off offset:528
	s_cbranch_execz .LBB0_1533
	s_branch .LBB0_1534

.LBB0_1594:
	global_store_dwordx4 v[34:35], v[24:27], off offset:16
	s_cbranch_execz .LBB0_1539

.LBB0_1598:
	global_store_dwordx4 v[34:35], v[16:19], off offset:528
	s_cbranch_execz .LBB0_1543
	s_branch .LBB0_1544

.LBB0_1600:
	global_store_dwordx4 v[18:19], v[8:11], off offset:16
	s_cbranch_execz .LBB0_1549

.LBB0_1604:
	global_store_dwordx4 v[18:19], v[0:3], off offset:528
	s_cbranch_execz .LBB0_1553
	s_branch .LBB0_1554

.LBB0_1827:
	v_mov_b32_e32 v112, v180
	s_barrier
	v_mov_b32_e32 v130, v180
	v_ashrrev_i32_e32 v131, 2, v112
	v_and_b32_e32 v131, 0xffffffc0, v131
	v_add_u32_e32 v131, s31, v131
	s_mul_i32 s6, s14, 0x500
	v_and_or_b32 v132, v130, 15, v131
	v_add_u32_e32 v134, 0xffff8000, v132
	v_lshrrev_b32_e32 v112, 1, v112
	v_lshrrev_b32_e32 v130, 1, v130
	s_ashr_i32 s7, s6, 31
	v_ashrrev_i32_e32 v135, 31, v134
	v_and_b32_e32 v112, 0x60, v112
	v_and_b32_e32 v130, 24, v130
	v_lshl_add_u64 v[134:135], v[134:135], 0, s[6:7]
	v_or3_b32 v130, v112, v130, s30
	v_lshlrev_b64 v[134:135], 12, v[134:135]
	v_lshl_add_u64 v[134:135], s[74:75], 0, v[134:135]
	v_ashrrev_i32_e32 v131, 31, v130
	v_cmp_gt_i32_e64 s[2:3], s63, v132
	s_mov_b64 s[8:9], -1
	s_andn2_b64 vcc, exec, s[4:5]
	v_lshl_add_u64 v[138:139], v[130:131], 2, v[134:135]
	s_mov_b64 s[56:57], 0x1a8a9500
	s_cbranch_vccnz .Lmy_ffn_epi
	s_mov_b64 s[8:9], 0
	global_store_dwordx4 v[138:139], v[126:129], off

.LBB0_1834:
	s_mov_b64 s[8:9], -1
	s_and_b64 vcc, exec, s[4:5]
	s_cbranch_vccz .LBB0_1836
	global_store_dwordx4 v[138:139], v[122:125], off offset:16
	s_mov_b64 s[8:9], 0

.LBB0_1839:
	s_andn2_b64 vcc, exec, s[8:9]
	s_cbranch_vccnz .LBB0_1841
	v_mov_b32_e32 v112, s79
	v_mov_b32_e32 v126, s77
	v_cndmask_b32_e64 v127, v112, v126, s[2:3]
	v_mov_b32_e32 v112, s78
	v_mov_b32_e32 v126, s76
	v_cndmask_b32_e64 v126, v112, v126, s[2:3]
	v_lshl_add_u64 v[126:127], v[126:127], 0, v[134:135]
	v_lshl_add_u64 v[126:127], v[130:131], 2, v[126:127]
	global_store_dwordx4 v[126:127], v[122:125], off offset:16

.LBB0_1848:
	s_mov_b64 s[8:9], -1
	s_and_b64 vcc, exec, s[4:5]
	s_cbranch_vccz .LBB0_1850
	global_store_dwordx4 v[138:139], v[114:117], off offset:528
	s_mov_b64 s[8:9], 0

.LBB0_1853:
	s_andn2_b64 vcc, exec, s[8:9]
	s_cbranch_vccnz .LBB0_1855
	v_mov_b32_e32 v112, s79
	v_mov_b32_e32 v118, s77
	v_cndmask_b32_e64 v119, v112, v118, s[2:3]
	v_mov_b32_e32 v112, s78
	v_mov_b32_e32 v118, s76
	v_cndmask_b32_e64 v118, v112, v118, s[2:3]
	v_lshl_add_u64 v[118:119], v[118:119], 0, v[134:135]
	v_lshl_add_u64 v[118:119], v[130:131], 2, v[118:119]
	global_store_dwordx4 v[118:119], v[114:117], off offset:528

.LBB0_1862:
	s_mov_b64 s[8:9], -1
	s_and_b64 vcc, exec, s[4:5]
	s_cbranch_vccz .LBB0_1864
	global_store_dwordx4 v[118:119], v[104:107], off offset:16
	s_mov_b64 s[8:9], 0

.LBB0_1867:
	s_andn2_b64 vcc, exec, s[8:9]
	s_cbranch_vccnz .LBB0_1869
	v_mov_b32_e32 v108, s79
	v_mov_b32_e32 v109, s77
	v_cndmask_b32_e64 v109, v108, v109, s[2:3]
	v_mov_b32_e32 v108, s78
	v_mov_b32_e32 v110, s76
	v_cndmask_b32_e64 v108, v108, v110, s[2:3]
	v_lshl_add_u64 v[108:109], v[108:109], 0, v[114:115]
	v_lshl_add_u64 v[108:109], v[130:131], 2, v[108:109]
	global_store_dwordx4 v[108:109], v[104:107], off offset:16

.LBB0_1876:
	s_mov_b64 s[8:9], -1
	s_and_b64 vcc, exec, s[4:5]
	s_cbranch_vccz .LBB0_1878
	global_store_dwordx4 v[118:119], v[96:99], off offset:528
	s_mov_b64 s[8:9], 0

.LBB0_1881:
	s_andn2_b64 vcc, exec, s[8:9]
	s_cbranch_vccnz .LBB0_1883
	v_mov_b32_e32 v100, s79
	v_mov_b32_e32 v101, s77
	v_cndmask_b32_e64 v101, v100, v101, s[2:3]
	v_mov_b32_e32 v100, s78
	v_mov_b32_e32 v102, s76
	v_cndmask_b32_e64 v100, v100, v102, s[2:3]
	v_lshl_add_u64 v[100:101], v[100:101], 0, v[114:115]
	v_lshl_add_u64 v[100:101], v[130:131], 2, v[100:101]
	global_store_dwordx4 v[100:101], v[96:99], off offset:528

.LBB0_1890:
	s_mov_b64 s[8:9], -1
	s_and_b64 vcc, exec, s[4:5]
	s_cbranch_vccz .LBB0_1892
	global_store_dwordx4 v[100:101], v[88:91], off offset:16
	s_mov_b64 s[8:9], 0

.LBB0_1895:
	s_andn2_b64 vcc, exec, s[8:9]
	s_cbranch_vccnz .LBB0_1897
	v_mov_b32_e32 v92, s79
	v_mov_b32_e32 v93, s77
	v_cndmask_b32_e64 v93, v92, v93, s[2:3]
	v_mov_b32_e32 v92, s78
	v_mov_b32_e32 v94, s76
	v_cndmask_b32_e64 v92, v92, v94, s[2:3]
	v_lshl_add_u64 v[92:93], v[92:93], 0, v[96:97]
	v_lshl_add_u64 v[92:93], v[130:131], 2, v[92:93]
	global_store_dwordx4 v[92:93], v[88:91], off offset:16

.LBB0_1904:
	s_mov_b64 s[8:9], -1
	s_and_b64 vcc, exec, s[4:5]
	s_cbranch_vccz .LBB0_1906
	global_store_dwordx4 v[100:101], v[80:83], off offset:528
	s_mov_b64 s[8:9], 0

.LBB0_1909:
	s_andn2_b64 vcc, exec, s[8:9]
	s_cbranch_vccnz .LBB0_1911
	v_mov_b32_e32 v84, s79
	v_mov_b32_e32 v85, s77
	v_cndmask_b32_e64 v85, v84, v85, s[2:3]
	v_mov_b32_e32 v84, s78
	v_mov_b32_e32 v86, s76
	v_cndmask_b32_e64 v84, v84, v86, s[2:3]
	v_lshl_add_u64 v[84:85], v[84:85], 0, v[96:97]
	v_lshl_add_u64 v[84:85], v[130:131], 2, v[84:85]
	global_store_dwordx4 v[84:85], v[80:83], off offset:528

.LBB0_1918:
	s_mov_b64 s[8:9], -1
	s_and_b64 vcc, exec, s[4:5]
	s_cbranch_vccz .LBB0_1920
	global_store_dwordx4 v[84:85], v[72:75], off offset:16
	s_mov_b64 s[8:9], 0

.LBB0_1923:
	s_andn2_b64 vcc, exec, s[8:9]
	s_cbranch_vccnz .LBB0_1925
	v_mov_b32_e32 v76, s79
	v_mov_b32_e32 v77, s77
	v_cndmask_b32_e64 v77, v76, v77, s[2:3]
	v_mov_b32_e32 v76, s78
	v_mov_b32_e32 v78, s76
	v_cndmask_b32_e64 v76, v76, v78, s[2:3]
	v_lshl_add_u64 v[76:77], v[76:77], 0, v[80:81]
	v_lshl_add_u64 v[76:77], v[130:131], 2, v[76:77]
	global_store_dwordx4 v[76:77], v[72:75], off offset:16

.LBB0_1932:
	s_mov_b64 s[8:9], -1
	s_and_b64 vcc, exec, s[4:5]
	s_cbranch_vccz .LBB0_1934
	global_store_dwordx4 v[84:85], v[64:67], off offset:528
	s_mov_b64 s[8:9], 0

.LBB0_1937:
	s_andn2_b64 vcc, exec, s[8:9]
	s_cbranch_vccnz .LBB0_1939
	v_mov_b32_e32 v68, s79
	v_mov_b32_e32 v69, s77
	v_cndmask_b32_e64 v69, v68, v69, s[2:3]
	v_mov_b32_e32 v68, s78
	v_mov_b32_e32 v70, s76
	v_cndmask_b32_e64 v68, v68, v70, s[2:3]
	v_lshl_add_u64 v[68:69], v[68:69], 0, v[80:81]
	v_lshl_add_u64 v[68:69], v[130:131], 2, v[68:69]
	global_store_dwordx4 v[68:69], v[64:67], off offset:528

.LBB0_1946:
	s_mov_b64 s[8:9], -1
	s_and_b64 vcc, exec, s[4:5]
	s_cbranch_vccz .LBB0_1948
	global_store_dwordx4 v[68:69], v[56:59], off offset:16
	s_mov_b64 s[8:9], 0

.LBB0_1951:
	s_andn2_b64 vcc, exec, s[8:9]
	s_cbranch_vccnz .LBB0_1953
	v_mov_b32_e32 v60, s79
	v_mov_b32_e32 v61, s77
	v_cndmask_b32_e64 v61, v60, v61, s[2:3]
	v_mov_b32_e32 v60, s78
	v_mov_b32_e32 v62, s76
	v_cndmask_b32_e64 v60, v60, v62, s[2:3]
	v_lshl_add_u64 v[60:61], v[60:61], 0, v[64:65]
	v_lshl_add_u64 v[60:61], v[130:131], 2, v[60:61]
	global_store_dwordx4 v[60:61], v[56:59], off offset:16

.LBB0_1960:
	s_mov_b64 s[8:9], -1
	s_and_b64 vcc, exec, s[4:5]
	s_cbranch_vccz .LBB0_1962
	global_store_dwordx4 v[68:69], v[48:51], off offset:528
	s_mov_b64 s[8:9], 0

.LBB0_1965:
	s_andn2_b64 vcc, exec, s[8:9]
	s_cbranch_vccnz .LBB0_1967
	v_mov_b32_e32 v52, s79
	v_mov_b32_e32 v53, s77
	v_cndmask_b32_e64 v53, v52, v53, s[2:3]
	v_mov_b32_e32 v52, s78
	v_mov_b32_e32 v54, s76
	v_cndmask_b32_e64 v52, v52, v54, s[2:3]
	v_lshl_add_u64 v[52:53], v[52:53], 0, v[64:65]
	v_lshl_add_u64 v[52:53], v[130:131], 2, v[52:53]
	global_store_dwordx4 v[52:53], v[48:51], off offset:528

.LBB0_1974:
	s_mov_b64 s[8:9], -1
	s_and_b64 vcc, exec, s[4:5]
	s_cbranch_vccz .LBB0_1976
	global_store_dwordx4 v[52:53], v[40:43], off offset:16
	s_mov_b64 s[8:9], 0

.LBB0_1979:
	s_andn2_b64 vcc, exec, s[8:9]
	s_cbranch_vccnz .LBB0_1981
	v_mov_b32_e32 v44, s79
	v_mov_b32_e32 v45, s77
	v_cndmask_b32_e64 v45, v44, v45, s[2:3]
	v_mov_b32_e32 v44, s78
	v_mov_b32_e32 v46, s76
	v_cndmask_b32_e64 v44, v44, v46, s[2:3]
	v_lshl_add_u64 v[44:45], v[44:45], 0, v[48:49]
	v_lshl_add_u64 v[44:45], v[130:131], 2, v[44:45]
	global_store_dwordx4 v[44:45], v[40:43], off offset:16

.LBB0_1988:
	s_mov_b64 s[8:9], -1
	s_and_b64 vcc, exec, s[4:5]
	s_cbranch_vccz .LBB0_1990
	global_store_dwordx4 v[52:53], v[32:35], off offset:528
	s_mov_b64 s[8:9], 0

.LBB0_1993:
	s_andn2_b64 vcc, exec, s[8:9]
	s_cbranch_vccnz .LBB0_1995
	v_mov_b32_e32 v36, s79
	v_mov_b32_e32 v37, s77
	v_cndmask_b32_e64 v37, v36, v37, s[2:3]
	v_mov_b32_e32 v36, s78
	v_mov_b32_e32 v38, s76
	v_cndmask_b32_e64 v36, v36, v38, s[2:3]
	v_lshl_add_u64 v[36:37], v[36:37], 0, v[48:49]
	v_lshl_add_u64 v[36:37], v[130:131], 2, v[36:37]
	global_store_dwordx4 v[36:37], v[32:35], off offset:528

.LBB0_2002:
	s_mov_b64 s[8:9], -1
	s_and_b64 vcc, exec, s[4:5]
	s_cbranch_vccz .LBB0_2004
	global_store_dwordx4 v[36:37], v[24:27], off offset:16
	s_mov_b64 s[8:9], 0

.LBB0_2007:
	s_andn2_b64 vcc, exec, s[8:9]
	s_cbranch_vccnz .LBB0_2009
	v_mov_b32_e32 v28, s79
	v_mov_b32_e32 v29, s77
	v_cndmask_b32_e64 v29, v28, v29, s[2:3]
	v_mov_b32_e32 v28, s78
	v_mov_b32_e32 v30, s76
	v_cndmask_b32_e64 v28, v28, v30, s[2:3]
	v_lshl_add_u64 v[28:29], v[28:29], 0, v[32:33]
	v_lshl_add_u64 v[28:29], v[130:131], 2, v[28:29]
	global_store_dwordx4 v[28:29], v[24:27], off offset:16

.LBB0_2016:
	s_mov_b64 s[8:9], -1
	s_and_b64 vcc, exec, s[4:5]
	s_cbranch_vccz .LBB0_2018
	global_store_dwordx4 v[36:37], v[16:19], off offset:528
	s_mov_b64 s[8:9], 0

.LBB0_2021:
	s_andn2_b64 vcc, exec, s[8:9]
	s_cbranch_vccnz .LBB0_2023
	v_mov_b32_e32 v20, s79
	v_mov_b32_e32 v21, s77
	v_cndmask_b32_e64 v21, v20, v21, s[2:3]
	v_mov_b32_e32 v20, s78
	v_mov_b32_e32 v22, s76
	v_cndmask_b32_e64 v20, v20, v22, s[2:3]
	v_lshl_add_u64 v[20:21], v[20:21], 0, v[32:33]
	v_lshl_add_u64 v[20:21], v[130:131], 2, v[20:21]
	global_store_dwordx4 v[20:21], v[16:19], off offset:528

.LBB0_2030:
	s_mov_b64 s[6:7], -1
	s_and_b64 vcc, exec, s[4:5]
	s_cbranch_vccz .LBB0_2032
	global_store_dwordx4 v[20:21], v[8:11], off offset:16
	s_mov_b64 s[6:7], 0

.LBB0_2035:
	s_andn2_b64 vcc, exec, s[6:7]
	s_cbranch_vccnz .LBB0_2037
	v_mov_b32_e32 v12, s79
	v_mov_b32_e32 v13, s77
	v_cndmask_b32_e64 v13, v12, v13, s[2:3]
	v_mov_b32_e32 v12, s78
	v_mov_b32_e32 v14, s76
	v_cndmask_b32_e64 v12, v12, v14, s[2:3]
	v_lshl_add_u64 v[12:13], v[12:13], 0, v[16:17]
	v_lshl_add_u64 v[12:13], v[130:131], 2, v[12:13]
	global_store_dwordx4 v[12:13], v[8:11], off offset:16

.LBB0_2044:
	s_mov_b64 s[6:7], -1
	s_and_b64 vcc, exec, s[4:5]
	s_cbranch_vccz .LBB0_2046
	global_store_dwordx4 v[20:21], v[0:3], off offset:528
	s_mov_b64 s[6:7], 0

.LBB0_2049:
	s_andn2_b64 vcc, exec, s[4:5]
	s_cbranch_vccnz .LBB0_2051
	v_mov_b32_e32 v4, s79
	v_mov_b32_e32 v5, s77
	v_cndmask_b32_e64 v5, v4, v5, s[2:3]
	v_mov_b32_e32 v4, s78
	v_mov_b32_e32 v6, s76
	v_cndmask_b32_e64 v4, v4, v6, s[2:3]
	v_lshl_add_u64 v[4:5], v[4:5], 0, v[16:17]
	v_lshl_add_u64 v[4:5], v[130:131], 2, v[4:5]
	global_store_dwordx4 v[4:5], v[0:3], off offset:528

.Lmy_ffn_epi:
	v_lshlrev_b32_e32 v134, 11, v132
	v_lshl_add_u32 v134, v130, 1, v134
	v_add_u32_e32 v135, 0x8000, v134
	v_add_u32_e32 v136, 0x10000, v134
	v_add_u32_e32 v137, 0x18000, v134
	v_add_u32_e32 v140, 0x40000, v134
	v_add_u32_e32 v141, 0x48000, v134
	v_add_u32_e32 v112, 0x50000, v134
	v_add_u32_e32 v133, 0x58000, v134
	global_load_dwordx4 v[192:195], v134, s[26:27]
	global_load_dwordx4 v[196:199], v134, s[26:27] offset:256
	global_load_dwordx4 v[200:203], v135, s[26:27]
	global_load_dwordx4 v[204:207], v135, s[26:27] offset:256
	global_load_dwordx4 v[208:211], v136, s[26:27]
	global_load_dwordx4 v[212:215], v136, s[26:27] offset:256
	global_load_dwordx4 v[216:219], v137, s[26:27]
	global_load_dwordx4 v[220:223], v137, s[26:27] offset:256
	global_load_dwordx4 v[224:227], v140, s[26:27]
	global_load_dwordx4 v[228:231], v140, s[26:27] offset:256
	global_load_dwordx4 v[232:235], v141, s[26:27]
	global_load_dwordx4 v[236:239], v141, s[26:27] offset:256
	global_load_dwordx4 v[240:243], v112, s[26:27]
	global_load_dwordx4 v[244:247], v112, s[26:27] offset:256
	global_load_dwordx4 v[248:251], v133, s[26:27]
	global_load_dwordx4 v[174:177], v133, s[26:27] offset:256
	s_waitcnt vmcnt(15)
	v_lshlrev_b32_e32 v178, 16, v192
	v_and_b32_e32 v179, 0xffff0000, v192
	v_pk_add_f32 v[126:127], v[126:127], v[178:179]
	v_lshlrev_b32_e32 v178, 16, v193
	v_and_b32_e32 v179, 0xffff0000, v193
	v_pk_add_f32 v[128:129], v[128:129], v[178:179]
	v_lshlrev_b32_e32 v178, 16, v194
	v_and_b32_e32 v179, 0xffff0000, v194
	v_pk_add_f32 v[122:123], v[122:123], v[178:179]
	v_lshlrev_b32_e32 v178, 16, v195
	v_and_b32_e32 v179, 0xffff0000, v195
	v_pk_add_f32 v[124:125], v[124:125], v[178:179]
	s_waitcnt vmcnt(14)
	v_lshlrev_b32_e32 v178, 16, v196
	v_and_b32_e32 v179, 0xffff0000, v196
	v_pk_add_f32 v[118:119], v[118:119], v[178:179]
	v_lshlrev_b32_e32 v178, 16, v197
	v_and_b32_e32 v179, 0xffff0000, v197
	v_pk_add_f32 v[120:121], v[120:121], v[178:179]
	v_lshlrev_b32_e32 v178, 16, v198
	v_and_b32_e32 v179, 0xffff0000, v198
	v_pk_add_f32 v[114:115], v[114:115], v[178:179]
	v_lshlrev_b32_e32 v178, 16, v199
	v_and_b32_e32 v179, 0xffff0000, v199
	v_pk_add_f32 v[116:117], v[116:117], v[178:179]
	s_waitcnt vmcnt(13)
	v_lshlrev_b32_e32 v178, 16, v200
	v_and_b32_e32 v179, 0xffff0000, v200
	v_pk_add_f32 v[108:109], v[108:109], v[178:179]
	v_lshlrev_b32_e32 v178, 16, v201
	v_and_b32_e32 v179, 0xffff0000, v201
	v_pk_add_f32 v[110:111], v[110:111], v[178:179]
	v_lshlrev_b32_e32 v178, 16, v202
	v_and_b32_e32 v179, 0xffff0000, v202
	v_pk_add_f32 v[104:105], v[104:105], v[178:179]
	v_lshlrev_b32_e32 v178, 16, v203
	v_and_b32_e32 v179, 0xffff0000, v203
	v_pk_add_f32 v[106:107], v[106:107], v[178:179]
	s_waitcnt vmcnt(12)
	v_lshlrev_b32_e32 v178, 16, v204
	v_and_b32_e32 v179, 0xffff0000, v204
	v_pk_add_f32 v[100:101], v[100:101], v[178:179]
	v_lshlrev_b32_e32 v178, 16, v205
	v_and_b32_e32 v179, 0xffff0000, v205
	v_pk_add_f32 v[102:103], v[102:103], v[178:179]
	v_lshlrev_b32_e32 v178, 16, v206
	v_and_b32_e32 v179, 0xffff0000, v206
	v_pk_add_f32 v[96:97], v[96:97], v[178:179]
	v_lshlrev_b32_e32 v178, 16, v207
	v_and_b32_e32 v179, 0xffff0000, v207
	v_pk_add_f32 v[98:99], v[98:99], v[178:179]
	s_waitcnt vmcnt(11)
	v_lshlrev_b32_e32 v178, 16, v208
	v_and_b32_e32 v179, 0xffff0000, v208
	v_pk_add_f32 v[92:93], v[92:93], v[178:179]
	v_lshlrev_b32_e32 v178, 16, v209
	v_and_b32_e32 v179, 0xffff0000, v209
	v_pk_add_f32 v[94:95], v[94:95], v[178:179]
	v_lshlrev_b32_e32 v178, 16, v210
	v_and_b32_e32 v179, 0xffff0000, v210
	v_pk_add_f32 v[88:89], v[88:89], v[178:179]
	v_lshlrev_b32_e32 v178, 16, v211
	v_and_b32_e32 v179, 0xffff0000, v211
	v_pk_add_f32 v[90:91], v[90:91], v[178:179]
	s_waitcnt vmcnt(10)
	v_lshlrev_b32_e32 v178, 16, v212
	v_and_b32_e32 v179, 0xffff0000, v212
	v_pk_add_f32 v[84:85], v[84:85], v[178:179]
	v_lshlrev_b32_e32 v178, 16, v213
	v_and_b32_e32 v179, 0xffff0000, v213
	v_pk_add_f32 v[86:87], v[86:87], v[178:179]
	v_lshlrev_b32_e32 v178, 16, v214
	v_and_b32_e32 v179, 0xffff0000, v214
	v_pk_add_f32 v[80:81], v[80:81], v[178:179]
	v_lshlrev_b32_e32 v178, 16, v215
	v_and_b32_e32 v179, 0xffff0000, v215
	v_pk_add_f32 v[82:83], v[82:83], v[178:179]
	s_waitcnt vmcnt(9)
	v_lshlrev_b32_e32 v178, 16, v216
	v_and_b32_e32 v179, 0xffff0000, v216
	v_pk_add_f32 v[76:77], v[76:77], v[178:179]
	v_lshlrev_b32_e32 v178, 16, v217
	v_and_b32_e32 v179, 0xffff0000, v217
	v_pk_add_f32 v[78:79], v[78:79], v[178:179]
	v_lshlrev_b32_e32 v178, 16, v218
	v_and_b32_e32 v179, 0xffff0000, v218
	v_pk_add_f32 v[72:73], v[72:73], v[178:179]
	v_lshlrev_b32_e32 v178, 16, v219
	v_and_b32_e32 v179, 0xffff0000, v219
	v_pk_add_f32 v[74:75], v[74:75], v[178:179]
	s_waitcnt vmcnt(8)
	v_lshlrev_b32_e32 v178, 16, v220
	v_and_b32_e32 v179, 0xffff0000, v220
	v_pk_add_f32 v[68:69], v[68:69], v[178:179]
	v_lshlrev_b32_e32 v178, 16, v221
	v_and_b32_e32 v179, 0xffff0000, v221
	v_pk_add_f32 v[70:71], v[70:71], v[178:179]
	v_lshlrev_b32_e32 v178, 16, v222
	v_and_b32_e32 v179, 0xffff0000, v222
	v_pk_add_f32 v[64:65], v[64:65], v[178:179]
	v_lshlrev_b32_e32 v178, 16, v223
	v_and_b32_e32 v179, 0xffff0000, v223
	v_pk_add_f32 v[66:67], v[66:67], v[178:179]
	s_waitcnt vmcnt(7)
	v_lshlrev_b32_e32 v178, 16, v224
	v_and_b32_e32 v179, 0xffff0000, v224
	v_pk_add_f32 v[60:61], v[60:61], v[178:179]
	v_lshlrev_b32_e32 v178, 16, v225
	v_and_b32_e32 v179, 0xffff0000, v225
	v_pk_add_f32 v[62:63], v[62:63], v[178:179]
	v_lshlrev_b32_e32 v178, 16, v226
	v_and_b32_e32 v179, 0xffff0000, v226
	v_pk_add_f32 v[56:57], v[56:57], v[178:179]
	v_lshlrev_b32_e32 v178, 16, v227
	v_and_b32_e32 v179, 0xffff0000, v227
	v_pk_add_f32 v[58:59], v[58:59], v[178:179]
	s_waitcnt vmcnt(6)
	v_lshlrev_b32_e32 v178, 16, v228
	v_and_b32_e32 v179, 0xffff0000, v228
	v_pk_add_f32 v[52:53], v[52:53], v[178:179]
	v_lshlrev_b32_e32 v178, 16, v229
	v_and_b32_e32 v179, 0xffff0000, v229
	v_pk_add_f32 v[54:55], v[54:55], v[178:179]
	v_lshlrev_b32_e32 v178, 16, v230
	v_and_b32_e32 v179, 0xffff0000, v230
	v_pk_add_f32 v[48:49], v[48:49], v[178:179]
	v_lshlrev_b32_e32 v178, 16, v231
	v_and_b32_e32 v179, 0xffff0000, v231
	v_pk_add_f32 v[50:51], v[50:51], v[178:179]
	s_waitcnt vmcnt(5)
	v_lshlrev_b32_e32 v178, 16, v232
	v_and_b32_e32 v179, 0xffff0000, v232
	v_pk_add_f32 v[44:45], v[44:45], v[178:179]
	v_lshlrev_b32_e32 v178, 16, v233
	v_and_b32_e32 v179, 0xffff0000, v233
	v_pk_add_f32 v[46:47], v[46:47], v[178:179]
	v_lshlrev_b32_e32 v178, 16, v234
	v_and_b32_e32 v179, 0xffff0000, v234
	v_pk_add_f32 v[40:41], v[40:41], v[178:179]
	v_lshlrev_b32_e32 v178, 16, v235
	v_and_b32_e32 v179, 0xffff0000, v235
	v_pk_add_f32 v[42:43], v[42:43], v[178:179]
	s_waitcnt vmcnt(4)
	v_lshlrev_b32_e32 v178, 16, v236
	v_and_b32_e32 v179, 0xffff0000, v236
	v_pk_add_f32 v[36:37], v[36:37], v[178:179]
	v_lshlrev_b32_e32 v178, 16, v237
	v_and_b32_e32 v179, 0xffff0000, v237
	v_pk_add_f32 v[38:39], v[38:39], v[178:179]
	v_lshlrev_b32_e32 v178, 16, v238
	v_and_b32_e32 v179, 0xffff0000, v238
	v_pk_add_f32 v[32:33], v[32:33], v[178:179]
	v_lshlrev_b32_e32 v178, 16, v239
	v_and_b32_e32 v179, 0xffff0000, v239
	v_pk_add_f32 v[34:35], v[34:35], v[178:179]
	s_waitcnt vmcnt(3)
	v_lshlrev_b32_e32 v178, 16, v240
	v_and_b32_e32 v179, 0xffff0000, v240
	v_pk_add_f32 v[28:29], v[28:29], v[178:179]
	v_lshlrev_b32_e32 v178, 16, v241
	v_and_b32_e32 v179, 0xffff0000, v241
	v_pk_add_f32 v[30:31], v[30:31], v[178:179]
	v_lshlrev_b32_e32 v178, 16, v242
	v_and_b32_e32 v179, 0xffff0000, v242
	v_pk_add_f32 v[24:25], v[24:25], v[178:179]
	v_lshlrev_b32_e32 v178, 16, v243
	v_and_b32_e32 v179, 0xffff0000, v243
	v_pk_add_f32 v[26:27], v[26:27], v[178:179]
	s_waitcnt vmcnt(2)
	v_lshlrev_b32_e32 v178, 16, v244
	v_and_b32_e32 v179, 0xffff0000, v244
	v_pk_add_f32 v[20:21], v[20:21], v[178:179]
	v_lshlrev_b32_e32 v178, 16, v245
	v_and_b32_e32 v179, 0xffff0000, v245
	v_pk_add_f32 v[22:23], v[22:23], v[178:179]
	v_lshlrev_b32_e32 v178, 16, v246
	v_and_b32_e32 v179, 0xffff0000, v246
	v_pk_add_f32 v[16:17], v[16:17], v[178:179]
	v_lshlrev_b32_e32 v178, 16, v247
	v_and_b32_e32 v179, 0xffff0000, v247
	v_pk_add_f32 v[18:19], v[18:19], v[178:179]
	s_waitcnt vmcnt(1)
	v_lshlrev_b32_e32 v178, 16, v248
	v_and_b32_e32 v179, 0xffff0000, v248
	v_pk_add_f32 v[12:13], v[12:13], v[178:179]
	v_lshlrev_b32_e32 v178, 16, v249
	v_and_b32_e32 v179, 0xffff0000, v249
	v_pk_add_f32 v[14:15], v[14:15], v[178:179]
	v_lshlrev_b32_e32 v178, 16, v250
	v_and_b32_e32 v179, 0xffff0000, v250
	v_pk_add_f32 v[8:9], v[8:9], v[178:179]
	v_lshlrev_b32_e32 v178, 16, v251
	v_and_b32_e32 v179, 0xffff0000, v251
	v_pk_add_f32 v[10:11], v[10:11], v[178:179]
	s_waitcnt vmcnt(0)
	v_lshlrev_b32_e32 v178, 16, v174
	v_and_b32_e32 v179, 0xffff0000, v174
	v_pk_add_f32 v[4:5], v[4:5], v[178:179]
	v_lshlrev_b32_e32 v178, 16, v175
	v_and_b32_e32 v179, 0xffff0000, v175
	v_pk_add_f32 v[6:7], v[6:7], v[178:179]
	v_lshlrev_b32_e32 v178, 16, v176
	v_and_b32_e32 v179, 0xffff0000, v176
	v_pk_add_f32 v[0:1], v[0:1], v[178:179]
	v_lshlrev_b32_e32 v178, 16, v177
	v_and_b32_e32 v179, 0xffff0000, v177
	v_pk_add_f32 v[2:3], v[2:3], v[178:179]
	s_and_b64 vcc, exec, s[0:1]
	s_cbranch_vccz .Lmy_ffn_f32
	v_cvt_pk_bf16_f32 v192, v126, v127
	v_cvt_pk_bf16_f32 v193, v128, v129
	v_cvt_pk_bf16_f32 v194, v122, v123
	v_cvt_pk_bf16_f32 v195, v124, v125
	global_store_dwordx4 v134, v[192:195], s[26:27]
	v_cvt_pk_bf16_f32 v196, v118, v119
	v_cvt_pk_bf16_f32 v197, v120, v121
	v_cvt_pk_bf16_f32 v198, v114, v115
	v_cvt_pk_bf16_f32 v199, v116, v117
	global_store_dwordx4 v134, v[196:199], s[26:27] offset:256
	v_cvt_pk_bf16_f32 v200, v108, v109
	v_cvt_pk_bf16_f32 v201, v110, v111
	v_cvt_pk_bf16_f32 v202, v104, v105
	v_cvt_pk_bf16_f32 v203, v106, v107
	global_store_dwordx4 v135, v[200:203], s[26:27]
	v_cvt_pk_bf16_f32 v204, v100, v101
	v_cvt_pk_bf16_f32 v205, v102, v103
	v_cvt_pk_bf16_f32 v206, v96, v97
	v_cvt_pk_bf16_f32 v207, v98, v99
	global_store_dwordx4 v135, v[204:207], s[26:27] offset:256
	v_cvt_pk_bf16_f32 v208, v92, v93
	v_cvt_pk_bf16_f32 v209, v94, v95
	v_cvt_pk_bf16_f32 v210, v88, v89
	v_cvt_pk_bf16_f32 v211, v90, v91
	global_store_dwordx4 v136, v[208:211], s[26:27]
	v_cvt_pk_bf16_f32 v212, v84, v85
	v_cvt_pk_bf16_f32 v213, v86, v87
	v_cvt_pk_bf16_f32 v214, v80, v81
	v_cvt_pk_bf16_f32 v215, v82, v83
	global_store_dwordx4 v136, v[212:215], s[26:27] offset:256
	v_cvt_pk_bf16_f32 v216, v76, v77
	v_cvt_pk_bf16_f32 v217, v78, v79
	v_cvt_pk_bf16_f32 v218, v72, v73
	v_cvt_pk_bf16_f32 v219, v74, v75
	global_store_dwordx4 v137, v[216:219], s[26:27]
	v_cvt_pk_bf16_f32 v220, v68, v69
	v_cvt_pk_bf16_f32 v221, v70, v71
	v_cvt_pk_bf16_f32 v222, v64, v65
	v_cvt_pk_bf16_f32 v223, v66, v67
	global_store_dwordx4 v137, v[220:223], s[26:27] offset:256
	v_cvt_pk_bf16_f32 v224, v60, v61
	v_cvt_pk_bf16_f32 v225, v62, v63
	v_cvt_pk_bf16_f32 v226, v56, v57
	v_cvt_pk_bf16_f32 v227, v58, v59
	global_store_dwordx4 v140, v[224:227], s[26:27]
	v_cvt_pk_bf16_f32 v228, v52, v53
	v_cvt_pk_bf16_f32 v229, v54, v55
	v_cvt_pk_bf16_f32 v230, v48, v49
	v_cvt_pk_bf16_f32 v231, v50, v51
	global_store_dwordx4 v140, v[228:231], s[26:27] offset:256
	v_cvt_pk_bf16_f32 v232, v44, v45
	v_cvt_pk_bf16_f32 v233, v46, v47
	v_cvt_pk_bf16_f32 v234, v40, v41
	v_cvt_pk_bf16_f32 v235, v42, v43
	global_store_dwordx4 v141, v[232:235], s[26:27]
	v_cvt_pk_bf16_f32 v236, v36, v37
	v_cvt_pk_bf16_f32 v237, v38, v39
	v_cvt_pk_bf16_f32 v238, v32, v33
	v_cvt_pk_bf16_f32 v239, v34, v35
	global_store_dwordx4 v141, v[236:239], s[26:27] offset:256
	v_cvt_pk_bf16_f32 v240, v28, v29
	v_cvt_pk_bf16_f32 v241, v30, v31
	v_cvt_pk_bf16_f32 v242, v24, v25
	v_cvt_pk_bf16_f32 v243, v26, v27
	global_store_dwordx4 v112, v[240:243], s[26:27]
	v_cvt_pk_bf16_f32 v244, v20, v21
	v_cvt_pk_bf16_f32 v245, v22, v23
	v_cvt_pk_bf16_f32 v246, v16, v17
	v_cvt_pk_bf16_f32 v247, v18, v19
	global_store_dwordx4 v112, v[244:247], s[26:27] offset:256
	v_cvt_pk_bf16_f32 v248, v12, v13
	v_cvt_pk_bf16_f32 v249, v14, v15
	v_cvt_pk_bf16_f32 v250, v8, v9
	v_cvt_pk_bf16_f32 v251, v10, v11
	global_store_dwordx4 v133, v[248:251], s[26:27]
	v_cvt_pk_bf16_f32 v174, v4, v5
	v_cvt_pk_bf16_f32 v175, v6, v7
	v_cvt_pk_bf16_f32 v176, v0, v1
	v_cvt_pk_bf16_f32 v177, v2, v3
	global_store_dwordx4 v133, v[174:177], s[26:27] offset:256
	s_branch .LBB0_2051
.Lmy_ffn_f32:
	v_lshlrev_b32_e32 v134, 1, v134
	v_lshlrev_b32_e32 v135, 1, v135
	v_lshlrev_b32_e32 v136, 1, v136
	v_lshlrev_b32_e32 v137, 1, v137
	v_lshlrev_b32_e32 v140, 1, v140
	v_lshlrev_b32_e32 v141, 1, v141
	v_lshlrev_b32_e32 v112, 1, v112
	v_lshlrev_b32_e32 v133, 1, v133
	global_store_dwordx4 v134, v[126:129], s[76:77]
	global_store_dwordx4 v134, v[122:125], s[76:77] offset:16
	global_store_dwordx4 v134, v[118:121], s[76:77] offset:512
	global_store_dwordx4 v134, v[114:117], s[76:77] offset:528
	global_store_dwordx4 v135, v[108:111], s[76:77]
	global_store_dwordx4 v135, v[104:107], s[76:77] offset:16
	global_store_dwordx4 v135, v[100:103], s[76:77] offset:512
	global_store_dwordx4 v135, v[96:99], s[76:77] offset:528
	global_store_dwordx4 v136, v[92:95], s[76:77]
	global_store_dwordx4 v136, v[88:91], s[76:77] offset:16
	global_store_dwordx4 v136, v[84:87], s[76:77] offset:512
	global_store_dwordx4 v136, v[80:83], s[76:77] offset:528
	global_store_dwordx4 v137, v[76:79], s[76:77]
	global_store_dwordx4 v137, v[72:75], s[76:77] offset:16
	global_store_dwordx4 v137, v[68:71], s[76:77] offset:512
	global_store_dwordx4 v137, v[64:67], s[76:77] offset:528
	global_store_dwordx4 v140, v[60:63], s[76:77]
	global_store_dwordx4 v140, v[56:59], s[76:77] offset:16
	global_store_dwordx4 v140, v[52:55], s[76:77] offset:512
	global_store_dwordx4 v140, v[48:51], s[76:77] offset:528
	global_store_dwordx4 v141, v[44:47], s[76:77]
	global_store_dwordx4 v141, v[40:43], s[76:77] offset:16
	global_store_dwordx4 v141, v[36:39], s[76:77] offset:512
	global_store_dwordx4 v141, v[32:35], s[76:77] offset:528
	global_store_dwordx4 v112, v[28:31], s[76:77]
	global_store_dwordx4 v112, v[24:27], s[76:77] offset:16
	global_store_dwordx4 v112, v[20:23], s[76:77] offset:512
	global_store_dwordx4 v112, v[16:19], s[76:77] offset:528
	global_store_dwordx4 v133, v[12:15], s[76:77]
	global_store_dwordx4 v133, v[8:11], s[76:77] offset:16
	global_store_dwordx4 v133, v[4:7], s[76:77] offset:512
	global_store_dwordx4 v133, v[0:3], s[76:77] offset:528
	s_branch .LBB0_2051

.LBB0_2114:
	s_or_b64 exec, exec, s[4:5]
	s_mov_b64 s[4:5], exec
	v_mbcnt_lo_u32_b32 v0, s4, 0
	v_mbcnt_hi_u32_b32 v0, s5, v0
	v_cmp_eq_u32_e32 vcc, 0, v0
	s_and_saveexec_b64 s[6:7], vcc
	s_cbranch_execnz .LBB0_2115
	s_getpc_b64 s[98:99]
